# EpiResid epilogues of the WO and down GEMMs: all 16 residual loads of a unit issued up front, per-group counted vmcnt instead of vmcnt(0) (no store-ack waits)
# speedup vs baseline: 1.0437x; 1.0049x over previous
.LBB0_1617:
	v_lshl_add_u32 v158, s26, 8, v160
	v_lshl_or_b32 v156, s28, 8, v162
	v_ashrrev_i32_e32 v159, 31, v158
	v_ashrrev_i32_e32 v157, 31, v156
	v_lshlrev_b64 v[154:155], 10, v[158:159]
	v_lshl_add_u64 v[154:155], v[154:155], 0, v[156:157]
	v_lshlrev_b64 v[154:155], 1, v[154:155]
	v_lshl_add_u64 v[28:29], v[156:157], 2, s[12:13]
	v_lshl_add_u64 v[164:165], s[0:1], 0, v[154:155]
	global_load_dwordx4 v[40:43], v[28:29], off offset:16
	global_load_dwordx4 v[44:47], v[28:29], off
	global_load_dwordx4 v[24:27], v[28:29], off offset:528
	s_nop 0
	global_load_dwordx4 v[28:31], v[28:29], off offset:512
	s_nop 0
	v_mov_b32_e32 v218, v164
	v_mov_b32_e32 v219, v165
	global_load_dwordx4 v[178:181], v[218:219], off
	global_load_dwordx4 v[182:185], v[218:219], off offset:256
	v_add_co_u32_e32 v222, vcc, 0x8000, v218
	s_nop 1
	v_addc_co_u32_e32 v223, vcc, 0, v219, vcc
	global_load_dwordx4 v[186:189], v[222:223], off
	global_load_dwordx4 v[190:193], v[222:223], off offset:256
	v_add_co_u32_e32 v222, vcc, 0x10000, v218
	s_nop 1
	v_addc_co_u32_e32 v223, vcc, 0, v219, vcc
	global_load_dwordx4 v[194:197], v[222:223], off
	global_load_dwordx4 v[198:201], v[222:223], off offset:256
	v_add_co_u32_e32 v222, vcc, 0x18000, v218
	s_nop 1
	v_addc_co_u32_e32 v223, vcc, 0, v219, vcc
	global_load_dwordx4 v[202:205], v[222:223], off
	global_load_dwordx4 v[206:209], v[222:223], off offset:256
	v_add_co_u32_e32 v222, vcc, 0x40000, v218
	s_nop 1
	v_addc_co_u32_e32 v223, vcc, 0, v219, vcc
	global_load_dwordx4 v[210:213], v[222:223], off
	global_load_dwordx4 v[214:217], v[222:223], off offset:256
	v_add_co_u32_e32 v222, vcc, 0x48000, v218
	s_nop 1
	v_addc_co_u32_e32 v223, vcc, 0, v219, vcc
	global_load_dwordx4 v[226:229], v[222:223], off
	global_load_dwordx4 v[230:233], v[222:223], off offset:256
	v_add_co_u32_e32 v222, vcc, 0x50000, v218
	s_nop 1
	v_addc_co_u32_e32 v223, vcc, 0, v219, vcc
	global_load_dwordx4 v[236:239], v[222:223], off
	global_load_dwordx4 v[240:243], v[222:223], off offset:256
	v_add_co_u32_e32 v222, vcc, 0x58000, v218
	s_nop 1
	v_addc_co_u32_e32 v223, vcc, 0, v219, vcc
	global_load_dwordx4 v[244:247], v[222:223], off
	global_load_dwordx4 v[248:251], v[222:223], off offset:256
	s_waitcnt vmcnt(15)
	v_mov_b32_e32 v164, v178
	v_mov_b32_e32 v165, v179
	v_mov_b32_e32 v166, v180
	v_mov_b32_e32 v167, v181
	v_lshlrev_b32_e32 v168, 16, v164
	v_and_b32_e32 v169, 0xffff0000, v164
	v_lshlrev_b32_e32 v164, 16, v165
	v_and_b32_e32 v165, 0xffff0000, v165
	v_lshlrev_b32_e32 v170, 16, v166
	v_and_b32_e32 v171, 0xffff0000, v166
	v_lshlrev_b32_e32 v166, 16, v167
	v_and_b32_e32 v167, 0xffff0000, v167
	v_pk_add_f32 v[142:143], v[142:143], v[164:165]
	v_pk_add_f32 v[140:141], v[140:141], v[168:169]
	v_pk_add_f32 v[164:165], v[138:139], v[166:167]
	v_pk_add_f32 v[166:167], v[136:137], v[170:171]
	v_cvt_pk_bf16_f32 v136, v140, v141
	v_cvt_pk_bf16_f32 v137, v142, v143
	v_cvt_pk_bf16_f32 v138, v166, v167
	v_cvt_pk_bf16_f32 v139, v164, v165
	v_lshl_add_u64 v[168:169], s[8:9], 0, v[154:155]
	global_store_dwordx4 v[168:169], v[136:139], off
	s_nop 1
	v_mul_f32_e32 v136, v141, v141
	v_mul_f32_e32 v137, v143, v143
	v_fmac_f32_e32 v136, v140, v140
	v_fmac_f32_e32 v137, v142, v142
	v_add_f32_e32 v136, v136, v137
	v_mul_f32_e32 v137, v167, v167
	v_mul_f32_e32 v138, v165, v165
	v_fmac_f32_e32 v137, v166, v166
	v_fmac_f32_e32 v138, v164, v164
	v_add_f32_e32 v137, v137, v138
	v_add_f32_e32 v138, v137, v136
	v_pk_mul_f32 v[136:137], v[44:45], v[140:141]
	s_nop 0
	v_cvt_pk_bf16_f32 v140, v136, v137
	v_pk_mul_f32 v[136:137], v[46:47], v[142:143]
	s_nop 0
	v_cvt_pk_bf16_f32 v141, v136, v137
	v_pk_mul_f32 v[136:137], v[40:41], v[166:167]
	s_nop 0
	v_cvt_pk_bf16_f32 v142, v136, v137
	v_pk_mul_f32 v[136:137], v[42:43], v[164:165]
	s_nop 0
	v_cvt_pk_bf16_f32 v143, v136, v137
	v_lshl_add_u64 v[136:137], s[10:11], 0, v[154:155]
	global_store_dwordx4 v[136:137], v[140:143], off
	v_or_b32_e32 v136, 0x100, v154
	v_mov_b32_e32 v137, v155
	v_lshl_add_u64 v[140:141], s[0:1], 0, v[136:137]
	v_lshl_add_u64 v[136:137], s[10:11], 0, v[136:137]
	s_waitcnt vmcnt(16)
	v_mov_b32_e32 v140, v182
	v_mov_b32_e32 v141, v183
	v_mov_b32_e32 v142, v184
	v_mov_b32_e32 v143, v185
	v_lshlrev_b32_e32 v164, 16, v140
	v_and_b32_e32 v165, 0xffff0000, v140
	v_lshlrev_b32_e32 v140, 16, v141
	v_and_b32_e32 v141, 0xffff0000, v141
	v_lshlrev_b32_e32 v166, 16, v142
	v_and_b32_e32 v167, 0xffff0000, v142
	v_lshlrev_b32_e32 v142, 16, v143
	v_and_b32_e32 v143, 0xffff0000, v143
	v_pk_add_f32 v[134:135], v[134:135], v[140:141]
	v_pk_add_f32 v[132:133], v[132:133], v[164:165]
	v_pk_add_f32 v[130:131], v[130:131], v[142:143]
	v_pk_add_f32 v[128:129], v[128:129], v[166:167]
	v_cvt_pk_bf16_f32 v140, v132, v133
	v_cvt_pk_bf16_f32 v141, v134, v135
	v_cvt_pk_bf16_f32 v142, v128, v129
	v_cvt_pk_bf16_f32 v143, v130, v131
	global_store_dwordx4 v[168:169], v[140:143], off offset:256
	v_pk_mul_f32 v[164:165], v[26:27], v[130:131]
	s_nop 0
	v_pk_mul_f32 v[140:141], v[28:29], v[132:133]
	v_pk_mul_f32 v[142:143], v[30:31], v[134:135]
	v_cvt_pk_bf16_f32 v140, v140, v141
	v_cvt_pk_bf16_f32 v141, v142, v143
	v_pk_mul_f32 v[142:143], v[24:25], v[128:129]
	v_mul_f32_e32 v133, v133, v133
	v_mul_f32_e32 v129, v129, v129
	v_fmac_f32_e32 v133, v132, v132
	v_mul_f32_e32 v132, v135, v135
	v_fmac_f32_e32 v129, v128, v128
	v_mul_f32_e32 v128, v131, v131
	v_cvt_pk_bf16_f32 v142, v142, v143
	v_cvt_pk_bf16_f32 v143, v164, v165
	v_fmac_f32_e32 v132, v134, v134
	v_fmac_f32_e32 v128, v130, v130
	global_store_dwordx4 v[136:137], v[140:143], off
	v_add_f32_e32 v132, v133, v132
	v_add_f32_e32 v128, v129, v128
	v_mbcnt_lo_u32_b32 v129, -1, 0
	v_mbcnt_hi_u32_b32 v129, -1, v129
	v_add_f32_e32 v128, v128, v132
	v_lshlrev_b32_e32 v129, 2, v129
	v_add_f32_e32 v128, v138, v128
	v_xor_b32_e32 v129, 64, v129
	ds_bpermute_b32 v129, v129, v128
	s_waitcnt lgkmcnt(0)
	v_add_f32_e32 v130, v128, v129
	v_mbcnt_lo_u32_b32 v128, -1, 0
	v_mbcnt_hi_u32_b32 v128, -1, v128
	s_nop 0
	v_lshlrev_b32_e32 v128, 2, v128
	v_xor_b32_e32 v128, 0x80, v128
	ds_bpermute_b32 v131, v128, v130
	v_lshl_add_u64 v[128:129], v[158:159], 2, s[14:15]
	s_and_saveexec_b64 s[26:27], s[2:3]
	s_cbranch_execz .LBB0_1619
	s_waitcnt lgkmcnt(0)
	v_add_f32_e32 v130, v130, v131
	flat_atomic_add_f32 v[128:129], v130
.LBB0_1619:
	s_or_b64 exec, exec, s[26:27]
	v_or_b32_e32 v130, 16, v158
	s_waitcnt lgkmcnt(0)
	v_ashrrev_i32_e32 v131, 31, v130
	v_lshlrev_b64 v[130:131], 10, v[130:131]
	v_lshl_add_u64 v[130:131], v[130:131], 0, v[156:157]
	v_lshlrev_b64 v[130:131], 1, v[130:131]
	v_lshl_add_u64 v[132:133], s[0:1], 0, v[130:131]
	s_waitcnt vmcnt(17)
	v_mov_b32_e32 v132, v186
	v_mov_b32_e32 v133, v187
	v_mov_b32_e32 v134, v188
	v_mov_b32_e32 v135, v189
	v_lshlrev_b32_e32 v136, 16, v132
	v_and_b32_e32 v137, 0xffff0000, v132
	v_lshlrev_b32_e32 v132, 16, v133
	v_and_b32_e32 v133, 0xffff0000, v133
	v_lshlrev_b32_e32 v138, 16, v134
	v_and_b32_e32 v139, 0xffff0000, v134
	v_lshlrev_b32_e32 v134, 16, v135
	v_and_b32_e32 v135, 0xffff0000, v135
	v_pk_add_f32 v[126:127], v[126:127], v[132:133]
	v_pk_add_f32 v[124:125], v[124:125], v[136:137]
	v_pk_add_f32 v[132:133], v[122:123], v[134:135]
	v_pk_add_f32 v[134:135], v[120:121], v[138:139]
	v_cvt_pk_bf16_f32 v120, v124, v125
	v_cvt_pk_bf16_f32 v121, v126, v127
	v_cvt_pk_bf16_f32 v122, v134, v135
	v_cvt_pk_bf16_f32 v123, v132, v133
	v_lshl_add_u64 v[136:137], s[8:9], 0, v[130:131]
	global_store_dwordx4 v[136:137], v[120:123], off
	s_nop 1
	v_mul_f32_e32 v120, v125, v125
	v_mul_f32_e32 v121, v127, v127
	v_fmac_f32_e32 v120, v124, v124
	v_fmac_f32_e32 v121, v126, v126
	v_add_f32_e32 v120, v120, v121
	v_mul_f32_e32 v121, v135, v135
	v_mul_f32_e32 v122, v133, v133
	v_fmac_f32_e32 v121, v134, v134
	v_fmac_f32_e32 v122, v132, v132
	v_add_f32_e32 v121, v121, v122
	v_pk_mul_f32 v[122:123], v[44:45], v[124:125]
	v_pk_mul_f32 v[124:125], v[46:47], v[126:127]
	v_cvt_pk_bf16_f32 v122, v122, v123
	v_cvt_pk_bf16_f32 v123, v124, v125
	v_pk_mul_f32 v[124:125], v[40:41], v[134:135]
	v_pk_mul_f32 v[126:127], v[42:43], v[132:133]
	v_cvt_pk_bf16_f32 v124, v124, v125
	v_cvt_pk_bf16_f32 v125, v126, v127
	v_lshl_add_u64 v[126:127], s[10:11], 0, v[130:131]
	v_or_b32_e32 v130, 0x100, v130
	global_store_dwordx4 v[126:127], v[122:125], off
	v_add_f32_e32 v120, v121, v120
	s_nop 0
	v_lshl_add_u64 v[122:123], s[0:1], 0, v[130:131]
	s_waitcnt vmcnt(18)
	v_mov_b32_e32 v122, v190
	v_mov_b32_e32 v123, v191
	v_mov_b32_e32 v124, v192
	v_mov_b32_e32 v125, v193
	v_lshlrev_b32_e32 v126, 16, v122
	v_and_b32_e32 v127, 0xffff0000, v122
	v_lshlrev_b32_e32 v122, 16, v123
	v_and_b32_e32 v123, 0xffff0000, v123
	v_lshlrev_b32_e32 v132, 16, v124
	v_and_b32_e32 v133, 0xffff0000, v124
	v_lshlrev_b32_e32 v124, 16, v125
	v_and_b32_e32 v125, 0xffff0000, v125
	v_pk_add_f32 v[118:119], v[118:119], v[122:123]
	v_pk_add_f32 v[116:117], v[116:117], v[126:127]
	v_pk_add_f32 v[114:115], v[114:115], v[124:125]
	v_pk_add_f32 v[112:113], v[112:113], v[132:133]
	v_cvt_pk_bf16_f32 v122, v116, v117
	v_cvt_pk_bf16_f32 v123, v118, v119
	v_cvt_pk_bf16_f32 v124, v112, v113
	v_cvt_pk_bf16_f32 v125, v114, v115
	global_store_dwordx4 v[136:137], v[122:125], off offset:256
	v_pk_mul_f32 v[126:127], v[26:27], v[114:115]
	s_nop 0
	v_pk_mul_f32 v[122:123], v[28:29], v[116:117]
	v_pk_mul_f32 v[124:125], v[30:31], v[118:119]
	v_cvt_pk_bf16_f32 v122, v122, v123
	v_cvt_pk_bf16_f32 v123, v124, v125
	v_pk_mul_f32 v[124:125], v[24:25], v[112:113]
	v_mul_f32_e32 v117, v117, v117
	v_mul_f32_e32 v113, v113, v113
	v_fmac_f32_e32 v117, v116, v116
	v_mul_f32_e32 v116, v119, v119
	v_fmac_f32_e32 v113, v112, v112
	v_mul_f32_e32 v112, v115, v115
	v_cvt_pk_bf16_f32 v124, v124, v125
	v_cvt_pk_bf16_f32 v125, v126, v127
	v_lshl_add_u64 v[126:127], s[10:11], 0, v[130:131]
	v_fmac_f32_e32 v116, v118, v118
	v_fmac_f32_e32 v112, v114, v114
	global_store_dwordx4 v[126:127], v[122:125], off
	v_add_f32_e32 v116, v117, v116
	v_add_f32_e32 v112, v113, v112
	v_mbcnt_lo_u32_b32 v113, -1, 0
	v_mbcnt_hi_u32_b32 v113, -1, v113
	v_add_f32_e32 v112, v112, v116
	v_lshlrev_b32_e32 v113, 2, v113
	v_add_f32_e32 v112, v120, v112
	v_xor_b32_e32 v113, 64, v113
	ds_bpermute_b32 v113, v113, v112
	s_waitcnt lgkmcnt(0)
	v_add_f32_e32 v112, v112, v113
	v_mbcnt_lo_u32_b32 v113, -1, 0
	v_mbcnt_hi_u32_b32 v113, -1, v113
	s_nop 0
	v_lshlrev_b32_e32 v113, 2, v113
	v_xor_b32_e32 v113, 0x80, v113
	ds_bpermute_b32 v113, v113, v112
	s_and_saveexec_b64 s[26:27], s[2:3]
	s_cbranch_execz .LBB0_1621
	s_waitcnt lgkmcnt(0)
	v_add_f32_e32 v112, v112, v113
	flat_atomic_add_f32 v[128:129], v112 offset:64
.LBB0_1621:
	s_or_b64 exec, exec, s[26:27]
	v_or_b32_e32 v112, 32, v158
	s_waitcnt lgkmcnt(0)
	v_ashrrev_i32_e32 v113, 31, v112
	v_lshlrev_b64 v[112:113], 10, v[112:113]
	v_lshl_add_u64 v[112:113], v[112:113], 0, v[156:157]
	v_lshlrev_b64 v[112:113], 1, v[112:113]
	v_lshl_add_u64 v[114:115], s[0:1], 0, v[112:113]
	s_waitcnt vmcnt(19)
	v_mov_b32_e32 v114, v194
	v_mov_b32_e32 v115, v195
	v_mov_b32_e32 v116, v196
	v_mov_b32_e32 v117, v197
	v_lshlrev_b32_e32 v118, 16, v114
	v_and_b32_e32 v119, 0xffff0000, v114
	v_lshlrev_b32_e32 v114, 16, v115
	v_and_b32_e32 v115, 0xffff0000, v115
	v_lshlrev_b32_e32 v120, 16, v116
	v_and_b32_e32 v121, 0xffff0000, v116
	v_lshlrev_b32_e32 v116, 16, v117
	v_and_b32_e32 v117, 0xffff0000, v117
	v_pk_add_f32 v[110:111], v[110:111], v[114:115]
	v_pk_add_f32 v[108:109], v[108:109], v[118:119]
	v_pk_add_f32 v[114:115], v[106:107], v[116:117]
	v_pk_add_f32 v[116:117], v[104:105], v[120:121]
	v_cvt_pk_bf16_f32 v104, v108, v109
	v_cvt_pk_bf16_f32 v105, v110, v111
	v_cvt_pk_bf16_f32 v106, v116, v117
	v_cvt_pk_bf16_f32 v107, v114, v115
	v_lshl_add_u64 v[118:119], s[8:9], 0, v[112:113]
	global_store_dwordx4 v[118:119], v[104:107], off
	s_nop 1
	v_mul_f32_e32 v104, v109, v109
	v_mul_f32_e32 v105, v111, v111
	v_fmac_f32_e32 v104, v108, v108
	v_fmac_f32_e32 v105, v110, v110
	v_add_f32_e32 v104, v104, v105
	v_mul_f32_e32 v105, v117, v117
	v_mul_f32_e32 v106, v115, v115
	v_fmac_f32_e32 v105, v116, v116
	v_fmac_f32_e32 v106, v114, v114
	v_add_f32_e32 v105, v105, v106
	v_pk_mul_f32 v[106:107], v[44:45], v[108:109]
	v_pk_mul_f32 v[108:109], v[46:47], v[110:111]
	v_cvt_pk_bf16_f32 v106, v106, v107
	v_cvt_pk_bf16_f32 v107, v108, v109
	v_pk_mul_f32 v[108:109], v[40:41], v[116:117]
	v_pk_mul_f32 v[110:111], v[42:43], v[114:115]
	v_cvt_pk_bf16_f32 v108, v108, v109
	v_cvt_pk_bf16_f32 v109, v110, v111
	v_lshl_add_u64 v[110:111], s[10:11], 0, v[112:113]
	v_or_b32_e32 v112, 0x100, v112
	global_store_dwordx4 v[110:111], v[106:109], off
	v_add_f32_e32 v104, v105, v104
	s_nop 0
	v_lshl_add_u64 v[106:107], s[0:1], 0, v[112:113]
	s_waitcnt vmcnt(20)
	v_mov_b32_e32 v106, v198
	v_mov_b32_e32 v107, v199
	v_mov_b32_e32 v108, v200
	v_mov_b32_e32 v109, v201
	v_lshlrev_b32_e32 v110, 16, v106
	v_and_b32_e32 v111, 0xffff0000, v106
	v_lshlrev_b32_e32 v106, 16, v107
	v_and_b32_e32 v107, 0xffff0000, v107
	v_lshlrev_b32_e32 v114, 16, v108
	v_and_b32_e32 v115, 0xffff0000, v108
	v_lshlrev_b32_e32 v108, 16, v109
	v_and_b32_e32 v109, 0xffff0000, v109
	v_pk_add_f32 v[102:103], v[102:103], v[106:107]
	v_pk_add_f32 v[100:101], v[100:101], v[110:111]
	v_pk_add_f32 v[98:99], v[98:99], v[108:109]
	v_pk_add_f32 v[96:97], v[96:97], v[114:115]
	v_cvt_pk_bf16_f32 v106, v100, v101
	v_cvt_pk_bf16_f32 v107, v102, v103
	v_cvt_pk_bf16_f32 v108, v96, v97
	v_cvt_pk_bf16_f32 v109, v98, v99
	global_store_dwordx4 v[118:119], v[106:109], off offset:256
	v_pk_mul_f32 v[110:111], v[26:27], v[98:99]
	s_nop 0
	v_pk_mul_f32 v[106:107], v[28:29], v[100:101]
	v_pk_mul_f32 v[108:109], v[30:31], v[102:103]
	v_cvt_pk_bf16_f32 v106, v106, v107
	v_cvt_pk_bf16_f32 v107, v108, v109
	v_pk_mul_f32 v[108:109], v[24:25], v[96:97]
	v_mul_f32_e32 v101, v101, v101
	v_mul_f32_e32 v97, v97, v97
	v_fmac_f32_e32 v101, v100, v100
	v_mul_f32_e32 v100, v103, v103
	v_fmac_f32_e32 v97, v96, v96
	v_mul_f32_e32 v96, v99, v99
	v_cvt_pk_bf16_f32 v108, v108, v109
	v_cvt_pk_bf16_f32 v109, v110, v111
	v_lshl_add_u64 v[110:111], s[10:11], 0, v[112:113]
	v_fmac_f32_e32 v100, v102, v102
	v_fmac_f32_e32 v96, v98, v98
	global_store_dwordx4 v[110:111], v[106:109], off
	v_add_f32_e32 v100, v101, v100
	v_add_f32_e32 v96, v97, v96
	v_mbcnt_lo_u32_b32 v97, -1, 0
	v_mbcnt_hi_u32_b32 v97, -1, v97
	v_add_f32_e32 v96, v96, v100
	v_lshlrev_b32_e32 v97, 2, v97
	v_add_f32_e32 v96, v104, v96
	v_xor_b32_e32 v97, 64, v97
	ds_bpermute_b32 v97, v97, v96
	s_waitcnt lgkmcnt(0)
	v_add_f32_e32 v96, v96, v97
	v_mbcnt_lo_u32_b32 v97, -1, 0
	v_mbcnt_hi_u32_b32 v97, -1, v97
	s_nop 0
	v_lshlrev_b32_e32 v97, 2, v97
	v_xor_b32_e32 v97, 0x80, v97
	ds_bpermute_b32 v97, v97, v96
	s_and_saveexec_b64 s[26:27], s[2:3]
	s_cbranch_execz .LBB0_1623
	s_waitcnt lgkmcnt(0)
	v_add_f32_e32 v96, v96, v97
	flat_atomic_add_f32 v[128:129], v96 offset:128
.LBB0_1623:
	s_or_b64 exec, exec, s[26:27]
	v_or_b32_e32 v96, 48, v158
	s_waitcnt lgkmcnt(0)
	v_ashrrev_i32_e32 v97, 31, v96
	v_lshlrev_b64 v[96:97], 10, v[96:97]
	v_lshl_add_u64 v[96:97], v[96:97], 0, v[156:157]
	v_lshlrev_b64 v[96:97], 1, v[96:97]
	v_lshl_add_u64 v[98:99], s[0:1], 0, v[96:97]
	s_waitcnt vmcnt(21)
	v_mov_b32_e32 v98, v202
	v_mov_b32_e32 v99, v203
	v_mov_b32_e32 v100, v204
	v_mov_b32_e32 v101, v205
	v_lshlrev_b32_e32 v102, 16, v98
	v_and_b32_e32 v103, 0xffff0000, v98
	v_lshlrev_b32_e32 v98, 16, v99
	v_and_b32_e32 v99, 0xffff0000, v99
	v_lshlrev_b32_e32 v104, 16, v100
	v_and_b32_e32 v105, 0xffff0000, v100
	v_lshlrev_b32_e32 v100, 16, v101
	v_and_b32_e32 v101, 0xffff0000, v101
	v_pk_add_f32 v[94:95], v[94:95], v[98:99]
	v_pk_add_f32 v[92:93], v[92:93], v[102:103]
	v_pk_add_f32 v[98:99], v[90:91], v[100:101]
	v_pk_add_f32 v[100:101], v[88:89], v[104:105]
	v_cvt_pk_bf16_f32 v88, v92, v93
	v_cvt_pk_bf16_f32 v89, v94, v95
	v_cvt_pk_bf16_f32 v90, v100, v101
	v_cvt_pk_bf16_f32 v91, v98, v99
	v_lshl_add_u64 v[102:103], s[8:9], 0, v[96:97]
	global_store_dwordx4 v[102:103], v[88:91], off
	s_nop 1
	v_mul_f32_e32 v88, v93, v93
	v_mul_f32_e32 v89, v95, v95
	v_fmac_f32_e32 v88, v92, v92
	v_fmac_f32_e32 v89, v94, v94
	v_add_f32_e32 v88, v88, v89
	v_mul_f32_e32 v89, v101, v101
	v_mul_f32_e32 v90, v99, v99
	v_fmac_f32_e32 v89, v100, v100
	v_fmac_f32_e32 v90, v98, v98
	v_add_f32_e32 v89, v89, v90
	v_pk_mul_f32 v[90:91], v[44:45], v[92:93]
	v_pk_mul_f32 v[92:93], v[46:47], v[94:95]
	v_cvt_pk_bf16_f32 v90, v90, v91
	v_cvt_pk_bf16_f32 v91, v92, v93
	v_pk_mul_f32 v[92:93], v[40:41], v[100:101]
	v_pk_mul_f32 v[94:95], v[42:43], v[98:99]
	v_cvt_pk_bf16_f32 v92, v92, v93
	v_cvt_pk_bf16_f32 v93, v94, v95
	v_lshl_add_u64 v[94:95], s[10:11], 0, v[96:97]
	v_or_b32_e32 v96, 0x100, v96
	global_store_dwordx4 v[94:95], v[90:93], off
	v_add_f32_e32 v88, v89, v88
	s_nop 0
	v_lshl_add_u64 v[90:91], s[0:1], 0, v[96:97]
	s_waitcnt vmcnt(22)
	v_mov_b32_e32 v90, v206
	v_mov_b32_e32 v91, v207
	v_mov_b32_e32 v92, v208
	v_mov_b32_e32 v93, v209
	v_lshlrev_b32_e32 v94, 16, v90
	v_and_b32_e32 v95, 0xffff0000, v90
	v_lshlrev_b32_e32 v90, 16, v91
	v_and_b32_e32 v91, 0xffff0000, v91
	v_lshlrev_b32_e32 v98, 16, v92
	v_and_b32_e32 v99, 0xffff0000, v92
	v_lshlrev_b32_e32 v92, 16, v93
	v_and_b32_e32 v93, 0xffff0000, v93
	v_pk_add_f32 v[86:87], v[86:87], v[90:91]
	v_pk_add_f32 v[84:85], v[84:85], v[94:95]
	v_pk_add_f32 v[82:83], v[82:83], v[92:93]
	v_pk_add_f32 v[80:81], v[80:81], v[98:99]
	v_cvt_pk_bf16_f32 v90, v84, v85
	v_cvt_pk_bf16_f32 v91, v86, v87
	v_cvt_pk_bf16_f32 v92, v80, v81
	v_cvt_pk_bf16_f32 v93, v82, v83
	global_store_dwordx4 v[102:103], v[90:93], off offset:256
	v_pk_mul_f32 v[94:95], v[26:27], v[82:83]
	s_nop 0
	v_pk_mul_f32 v[90:91], v[28:29], v[84:85]
	v_pk_mul_f32 v[92:93], v[30:31], v[86:87]
	v_cvt_pk_bf16_f32 v90, v90, v91
	v_cvt_pk_bf16_f32 v91, v92, v93
	v_pk_mul_f32 v[92:93], v[24:25], v[80:81]
	v_mul_f32_e32 v85, v85, v85
	v_mul_f32_e32 v81, v81, v81
	v_fmac_f32_e32 v85, v84, v84
	v_mul_f32_e32 v84, v87, v87
	v_fmac_f32_e32 v81, v80, v80
	v_mul_f32_e32 v80, v83, v83
	v_cvt_pk_bf16_f32 v92, v92, v93
	v_cvt_pk_bf16_f32 v93, v94, v95
	v_lshl_add_u64 v[94:95], s[10:11], 0, v[96:97]
	v_fmac_f32_e32 v84, v86, v86
	v_fmac_f32_e32 v80, v82, v82
	global_store_dwordx4 v[94:95], v[90:93], off
	v_add_f32_e32 v84, v85, v84
	v_add_f32_e32 v80, v81, v80
	v_mbcnt_lo_u32_b32 v81, -1, 0
	v_mbcnt_hi_u32_b32 v81, -1, v81
	v_add_f32_e32 v80, v80, v84
	v_lshlrev_b32_e32 v81, 2, v81
	v_add_f32_e32 v80, v88, v80
	v_xor_b32_e32 v81, 64, v81
	ds_bpermute_b32 v81, v81, v80
	s_waitcnt lgkmcnt(0)
	v_add_f32_e32 v80, v80, v81
	v_mbcnt_lo_u32_b32 v81, -1, 0
	v_mbcnt_hi_u32_b32 v81, -1, v81
	s_nop 0
	v_lshlrev_b32_e32 v81, 2, v81
	v_xor_b32_e32 v81, 0x80, v81
	ds_bpermute_b32 v81, v81, v80
	s_and_saveexec_b64 s[26:27], s[2:3]
	s_cbranch_execz .LBB0_1625
	s_waitcnt lgkmcnt(0)
	v_add_f32_e32 v80, v80, v81
	flat_atomic_add_f32 v[128:129], v80 offset:192
.LBB0_1625:
	s_or_b64 exec, exec, s[26:27]
	s_mov_b64 s[26:27], 0x40000
	v_lshl_add_u64 v[84:85], v[154:155], 0, s[26:27]
	s_waitcnt lgkmcnt(0)
	v_lshl_add_u64 v[80:81], s[0:1], 0, v[84:85]
	s_mov_b64 s[26:27], 0x40100
	s_waitcnt vmcnt(23)
	v_mov_b32_e32 v80, v210
	v_mov_b32_e32 v81, v211
	v_mov_b32_e32 v82, v212
	v_mov_b32_e32 v83, v213
	v_lshlrev_b32_e32 v86, 16, v80
	v_and_b32_e32 v87, 0xffff0000, v80
	v_lshlrev_b32_e32 v80, 16, v81
	v_and_b32_e32 v81, 0xffff0000, v81
	v_lshlrev_b32_e32 v88, 16, v82
	v_and_b32_e32 v89, 0xffff0000, v82
	v_lshlrev_b32_e32 v82, 16, v83
	v_and_b32_e32 v83, 0xffff0000, v83
	v_pk_add_f32 v[80:81], v[78:79], v[80:81]
	v_pk_add_f32 v[78:79], v[76:77], v[86:87]
	v_pk_add_f32 v[82:83], v[74:75], v[82:83]
	v_pk_add_f32 v[86:87], v[72:73], v[88:89]
	v_cvt_pk_bf16_f32 v74, v78, v79
	v_cvt_pk_bf16_f32 v75, v80, v81
	v_cvt_pk_bf16_f32 v76, v86, v87
	v_cvt_pk_bf16_f32 v77, v82, v83
	v_lshl_add_u64 v[72:73], s[8:9], 0, v[84:85]
	global_store_dwordx4 v[72:73], v[74:77], off
	s_nop 1
	v_mul_f32_e32 v74, v79, v79
	v_mul_f32_e32 v75, v81, v81
	v_fmac_f32_e32 v74, v78, v78
	v_fmac_f32_e32 v75, v80, v80
	v_add_f32_e32 v74, v74, v75
	v_mul_f32_e32 v75, v87, v87
	v_mul_f32_e32 v76, v83, v83
	v_fmac_f32_e32 v75, v86, v86
	v_fmac_f32_e32 v76, v82, v82
	v_add_f32_e32 v75, v75, v76
	v_add_f32_e32 v76, v75, v74
	v_pk_mul_f32 v[74:75], v[44:45], v[78:79]
	s_nop 0
	v_cvt_pk_bf16_f32 v78, v74, v75
	v_pk_mul_f32 v[74:75], v[46:47], v[80:81]
	s_nop 0
	v_cvt_pk_bf16_f32 v79, v74, v75
	v_pk_mul_f32 v[74:75], v[40:41], v[86:87]
	s_nop 0
	v_cvt_pk_bf16_f32 v80, v74, v75
	v_pk_mul_f32 v[74:75], v[42:43], v[82:83]
	s_nop 0
	v_cvt_pk_bf16_f32 v81, v74, v75
	v_lshl_add_u64 v[74:75], s[10:11], 0, v[84:85]
	global_store_dwordx4 v[74:75], v[78:81], off
	v_lshl_add_u64 v[74:75], v[154:155], 0, s[26:27]
	s_nop 0
	v_lshl_add_u64 v[78:79], s[0:1], 0, v[74:75]
	s_waitcnt vmcnt(24)
	v_mov_b32_e32 v78, v214
	v_mov_b32_e32 v79, v215
	v_mov_b32_e32 v80, v216
	v_mov_b32_e32 v81, v217
	v_lshlrev_b32_e32 v82, 16, v78
	v_and_b32_e32 v83, 0xffff0000, v78
	v_lshlrev_b32_e32 v78, 16, v79
	v_and_b32_e32 v79, 0xffff0000, v79
	v_lshlrev_b32_e32 v84, 16, v80
	v_and_b32_e32 v85, 0xffff0000, v80
	v_lshlrev_b32_e32 v80, 16, v81
	v_and_b32_e32 v81, 0xffff0000, v81
	v_pk_add_f32 v[70:71], v[70:71], v[78:79]
	v_pk_add_f32 v[68:69], v[68:69], v[82:83]
	v_pk_add_f32 v[66:67], v[66:67], v[80:81]
	v_pk_add_f32 v[64:65], v[64:65], v[84:85]
	v_cvt_pk_bf16_f32 v78, v68, v69
	v_cvt_pk_bf16_f32 v79, v70, v71
	v_cvt_pk_bf16_f32 v80, v64, v65
	v_cvt_pk_bf16_f32 v81, v66, v67
	global_store_dwordx4 v[72:73], v[78:81], off offset:256
	v_pk_mul_f32 v[72:73], v[28:29], v[68:69]
	v_mul_f32_e32 v69, v69, v69
	v_cvt_pk_bf16_f32 v78, v72, v73
	v_pk_mul_f32 v[72:73], v[30:31], v[70:71]
	v_fmac_f32_e32 v69, v68, v68
	v_cvt_pk_bf16_f32 v79, v72, v73
	v_pk_mul_f32 v[72:73], v[24:25], v[64:65]
	v_mul_f32_e32 v65, v65, v65
	v_cvt_pk_bf16_f32 v80, v72, v73
	v_pk_mul_f32 v[72:73], v[26:27], v[66:67]
	v_mul_f32_e32 v68, v71, v71
	v_fmac_f32_e32 v65, v64, v64
	v_mul_f32_e32 v64, v67, v67
	v_cvt_pk_bf16_f32 v81, v72, v73
	v_lshl_add_u64 v[72:73], s[10:11], 0, v[74:75]
	v_fmac_f32_e32 v68, v70, v70
	v_fmac_f32_e32 v64, v66, v66
	global_store_dwordx4 v[72:73], v[78:81], off
	v_add_f32_e32 v68, v69, v68
	v_add_f32_e32 v64, v65, v64
	v_mbcnt_lo_u32_b32 v65, -1, 0
	v_mbcnt_hi_u32_b32 v65, -1, v65
	v_add_f32_e32 v64, v64, v68
	v_lshlrev_b32_e32 v65, 2, v65
	v_add_f32_e32 v64, v76, v64
	v_xor_b32_e32 v65, 64, v65
	ds_bpermute_b32 v65, v65, v64
	s_waitcnt lgkmcnt(0)
	v_add_f32_e32 v64, v64, v65
	v_mbcnt_lo_u32_b32 v65, -1, 0
	v_mbcnt_hi_u32_b32 v65, -1, v65
	s_nop 0
	v_lshlrev_b32_e32 v65, 2, v65
	v_xor_b32_e32 v65, 0x80, v65
	ds_bpermute_b32 v65, v65, v64
	s_and_saveexec_b64 s[26:27], s[2:3]
	s_cbranch_execz .LBB0_1627
	s_waitcnt lgkmcnt(0)
	v_add_f32_e32 v64, v64, v65
	flat_atomic_add_f32 v[128:129], v64 offset:512
.LBB0_1627:
	s_or_b64 exec, exec, s[26:27]
	s_mov_b64 s[26:27], 0x48000
	v_lshl_add_u64 v[68:69], v[154:155], 0, s[26:27]
	s_waitcnt lgkmcnt(0)
	v_lshl_add_u64 v[64:65], s[0:1], 0, v[68:69]
	s_mov_b64 s[26:27], 0x48100
	s_waitcnt vmcnt(25)
	v_mov_b32_e32 v64, v226
	v_mov_b32_e32 v65, v227
	v_mov_b32_e32 v66, v228
	v_mov_b32_e32 v67, v229
	v_lshlrev_b32_e32 v70, 16, v64
	v_and_b32_e32 v71, 0xffff0000, v64
	v_lshlrev_b32_e32 v64, 16, v65
	v_and_b32_e32 v65, 0xffff0000, v65
	v_lshlrev_b32_e32 v72, 16, v66
	v_and_b32_e32 v73, 0xffff0000, v66
	v_lshlrev_b32_e32 v66, 16, v67
	v_and_b32_e32 v67, 0xffff0000, v67
	v_pk_add_f32 v[64:65], v[62:63], v[64:65]
	v_pk_add_f32 v[62:63], v[60:61], v[70:71]
	v_pk_add_f32 v[66:67], v[58:59], v[66:67]
	v_pk_add_f32 v[70:71], v[56:57], v[72:73]
	v_cvt_pk_bf16_f32 v58, v62, v63
	v_cvt_pk_bf16_f32 v59, v64, v65
	v_cvt_pk_bf16_f32 v60, v70, v71
	v_cvt_pk_bf16_f32 v61, v66, v67
	v_lshl_add_u64 v[56:57], s[8:9], 0, v[68:69]
	global_store_dwordx4 v[56:57], v[58:61], off
	s_nop 1
	v_mul_f32_e32 v58, v63, v63
	v_mul_f32_e32 v59, v65, v65
	v_fmac_f32_e32 v58, v62, v62
	v_fmac_f32_e32 v59, v64, v64
	v_add_f32_e32 v58, v58, v59
	v_mul_f32_e32 v59, v71, v71
	v_mul_f32_e32 v60, v67, v67
	v_fmac_f32_e32 v59, v70, v70
	v_fmac_f32_e32 v60, v66, v66
	v_add_f32_e32 v59, v59, v60
	v_add_f32_e32 v60, v59, v58
	v_pk_mul_f32 v[58:59], v[44:45], v[62:63]
	s_nop 0
	v_cvt_pk_bf16_f32 v62, v58, v59
	v_pk_mul_f32 v[58:59], v[46:47], v[64:65]
	s_nop 0
	v_cvt_pk_bf16_f32 v63, v58, v59
	v_pk_mul_f32 v[58:59], v[40:41], v[70:71]
	s_nop 0
	v_cvt_pk_bf16_f32 v64, v58, v59
	v_pk_mul_f32 v[58:59], v[42:43], v[66:67]
	s_nop 0
	v_cvt_pk_bf16_f32 v65, v58, v59
	v_lshl_add_u64 v[58:59], s[10:11], 0, v[68:69]
	global_store_dwordx4 v[58:59], v[62:65], off
	v_lshl_add_u64 v[58:59], v[154:155], 0, s[26:27]
	s_nop 0
	v_lshl_add_u64 v[62:63], s[0:1], 0, v[58:59]
	s_waitcnt vmcnt(26)
	v_mov_b32_e32 v62, v230
	v_mov_b32_e32 v63, v231
	v_mov_b32_e32 v64, v232
	v_mov_b32_e32 v65, v233
	v_lshlrev_b32_e32 v66, 16, v62
	v_and_b32_e32 v67, 0xffff0000, v62
	v_lshlrev_b32_e32 v62, 16, v63
	v_and_b32_e32 v63, 0xffff0000, v63
	v_lshlrev_b32_e32 v68, 16, v64
	v_and_b32_e32 v69, 0xffff0000, v64
	v_lshlrev_b32_e32 v64, 16, v65
	v_and_b32_e32 v65, 0xffff0000, v65
	v_pk_add_f32 v[54:55], v[54:55], v[62:63]
	v_pk_add_f32 v[52:53], v[52:53], v[66:67]
	v_pk_add_f32 v[50:51], v[50:51], v[64:65]
	v_pk_add_f32 v[48:49], v[48:49], v[68:69]
	v_cvt_pk_bf16_f32 v62, v52, v53
	v_cvt_pk_bf16_f32 v63, v54, v55
	v_cvt_pk_bf16_f32 v64, v48, v49
	v_cvt_pk_bf16_f32 v65, v50, v51
	global_store_dwordx4 v[56:57], v[62:65], off offset:256
	v_pk_mul_f32 v[56:57], v[28:29], v[52:53]
	v_mul_f32_e32 v53, v53, v53
	v_cvt_pk_bf16_f32 v62, v56, v57
	v_pk_mul_f32 v[56:57], v[30:31], v[54:55]
	v_fmac_f32_e32 v53, v52, v52
	v_cvt_pk_bf16_f32 v63, v56, v57
	v_pk_mul_f32 v[56:57], v[24:25], v[48:49]
	v_mul_f32_e32 v49, v49, v49
	v_cvt_pk_bf16_f32 v64, v56, v57
	v_pk_mul_f32 v[56:57], v[26:27], v[50:51]
	v_mul_f32_e32 v52, v55, v55
	v_fmac_f32_e32 v49, v48, v48
	v_mul_f32_e32 v48, v51, v51
	v_cvt_pk_bf16_f32 v65, v56, v57
	v_lshl_add_u64 v[56:57], s[10:11], 0, v[58:59]
	v_fmac_f32_e32 v52, v54, v54
	v_fmac_f32_e32 v48, v50, v50
	global_store_dwordx4 v[56:57], v[62:65], off
	v_add_f32_e32 v52, v53, v52
	v_add_f32_e32 v48, v49, v48
	v_mbcnt_lo_u32_b32 v49, -1, 0
	v_mbcnt_hi_u32_b32 v49, -1, v49
	v_add_f32_e32 v48, v48, v52
	v_lshlrev_b32_e32 v49, 2, v49
	v_add_f32_e32 v48, v60, v48
	v_xor_b32_e32 v49, 64, v49
	ds_bpermute_b32 v49, v49, v48
	s_waitcnt lgkmcnt(0)
	v_add_f32_e32 v48, v48, v49
	v_mbcnt_lo_u32_b32 v49, -1, 0
	v_mbcnt_hi_u32_b32 v49, -1, v49
	s_nop 0
	v_lshlrev_b32_e32 v49, 2, v49
	v_xor_b32_e32 v49, 0x80, v49
	ds_bpermute_b32 v49, v49, v48
	s_and_saveexec_b64 s[26:27], s[2:3]
	s_cbranch_execz .LBB0_1629
	s_waitcnt lgkmcnt(0)
	v_add_f32_e32 v48, v48, v49
	flat_atomic_add_f32 v[128:129], v48 offset:576
.LBB0_1629:
	s_or_b64 exec, exec, s[26:27]
	s_mov_b64 s[26:27], 0x50000
	v_lshl_add_u64 v[52:53], v[154:155], 0, s[26:27]
	s_waitcnt lgkmcnt(0)
	v_lshl_add_u64 v[48:49], s[0:1], 0, v[52:53]
	s_mov_b64 s[26:27], 0x50100
	s_waitcnt vmcnt(27)
	v_mov_b32_e32 v48, v236
	v_mov_b32_e32 v49, v237
	v_mov_b32_e32 v50, v238
	v_mov_b32_e32 v51, v239
	v_lshlrev_b32_e32 v54, 16, v48
	v_and_b32_e32 v55, 0xffff0000, v48
	v_lshlrev_b32_e32 v48, 16, v49
	v_and_b32_e32 v49, 0xffff0000, v49
	v_lshlrev_b32_e32 v56, 16, v50
	v_and_b32_e32 v57, 0xffff0000, v50
	v_lshlrev_b32_e32 v50, 16, v51
	v_and_b32_e32 v51, 0xffff0000, v51
	v_pk_add_f32 v[38:39], v[38:39], v[48:49]
	v_pk_add_f32 v[48:49], v[36:37], v[54:55]
	v_pk_add_f32 v[54:55], v[34:35], v[50:51]
	v_pk_add_f32 v[50:51], v[32:33], v[56:57]
	v_cvt_pk_bf16_f32 v34, v48, v49
	v_cvt_pk_bf16_f32 v35, v38, v39
	v_cvt_pk_bf16_f32 v36, v50, v51
	v_cvt_pk_bf16_f32 v37, v54, v55
	v_lshl_add_u64 v[32:33], s[8:9], 0, v[52:53]
	global_store_dwordx4 v[32:33], v[34:37], off
	s_nop 1
	v_mul_f32_e32 v34, v49, v49
	v_mul_f32_e32 v35, v39, v39
	v_fmac_f32_e32 v34, v48, v48
	v_fmac_f32_e32 v35, v38, v38
	v_add_f32_e32 v34, v34, v35
	v_mul_f32_e32 v35, v51, v51
	v_mul_f32_e32 v36, v55, v55
	v_fmac_f32_e32 v35, v50, v50
	v_fmac_f32_e32 v36, v54, v54
	v_add_f32_e32 v35, v35, v36
	v_add_f32_e32 v36, v35, v34
	v_pk_mul_f32 v[34:35], v[44:45], v[48:49]
	s_nop 0
	v_cvt_pk_bf16_f32 v48, v34, v35
	v_pk_mul_f32 v[34:35], v[46:47], v[38:39]
	s_nop 0
	v_cvt_pk_bf16_f32 v49, v34, v35
	v_pk_mul_f32 v[34:35], v[40:41], v[50:51]
	s_nop 0
	v_cvt_pk_bf16_f32 v50, v34, v35
	v_pk_mul_f32 v[34:35], v[42:43], v[54:55]
	s_nop 0
	v_cvt_pk_bf16_f32 v51, v34, v35
	v_lshl_add_u64 v[34:35], s[10:11], 0, v[52:53]
	global_store_dwordx4 v[34:35], v[48:51], off
	v_lshl_add_u64 v[34:35], v[154:155], 0, s[26:27]
	v_lshl_add_u64 v[38:39], s[0:1], 0, v[34:35]
	s_waitcnt vmcnt(28)
	v_mov_b32_e32 v48, v240
	v_mov_b32_e32 v49, v241
	v_mov_b32_e32 v50, v242
	v_mov_b32_e32 v51, v243
	v_lshlrev_b32_e32 v38, 16, v48
	v_and_b32_e32 v39, 0xffff0000, v48
	v_lshlrev_b32_e32 v48, 16, v49
	v_and_b32_e32 v49, 0xffff0000, v49
	v_lshlrev_b32_e32 v52, 16, v50
	v_and_b32_e32 v53, 0xffff0000, v50
	v_lshlrev_b32_e32 v50, 16, v51
	v_and_b32_e32 v51, 0xffff0000, v51
	v_pk_add_f32 v[22:23], v[22:23], v[48:49]
	v_pk_add_f32 v[20:21], v[20:21], v[38:39]
	v_pk_add_f32 v[18:19], v[18:19], v[50:51]
	v_pk_add_f32 v[16:17], v[16:17], v[52:53]
	v_cvt_pk_bf16_f32 v48, v20, v21
	v_cvt_pk_bf16_f32 v49, v22, v23
	v_cvt_pk_bf16_f32 v50, v16, v17
	v_cvt_pk_bf16_f32 v51, v18, v19
	global_store_dwordx4 v[32:33], v[48:51], off offset:256
	v_pk_mul_f32 v[32:33], v[28:29], v[20:21]
	v_mul_f32_e32 v21, v21, v21
	v_cvt_pk_bf16_f32 v48, v32, v33
	v_pk_mul_f32 v[32:33], v[30:31], v[22:23]
	v_fmac_f32_e32 v21, v20, v20
	v_cvt_pk_bf16_f32 v49, v32, v33
	v_pk_mul_f32 v[32:33], v[24:25], v[16:17]
	v_mul_f32_e32 v17, v17, v17
	v_cvt_pk_bf16_f32 v50, v32, v33
	v_pk_mul_f32 v[32:33], v[26:27], v[18:19]
	v_mul_f32_e32 v20, v23, v23
	v_fmac_f32_e32 v17, v16, v16
	v_mul_f32_e32 v16, v19, v19
	v_cvt_pk_bf16_f32 v51, v32, v33
	v_lshl_add_u64 v[32:33], s[10:11], 0, v[34:35]
	v_fmac_f32_e32 v20, v22, v22
	v_fmac_f32_e32 v16, v18, v18
	global_store_dwordx4 v[32:33], v[48:51], off
	v_add_f32_e32 v20, v21, v20
	v_add_f32_e32 v16, v17, v16
	v_mbcnt_lo_u32_b32 v17, -1, 0
	v_mbcnt_hi_u32_b32 v17, -1, v17
	v_add_f32_e32 v16, v16, v20
	v_lshlrev_b32_e32 v17, 2, v17
	v_add_f32_e32 v16, v36, v16
	v_xor_b32_e32 v17, 64, v17
	ds_bpermute_b32 v17, v17, v16
	s_waitcnt lgkmcnt(0)
	v_add_f32_e32 v16, v16, v17
	v_mbcnt_lo_u32_b32 v17, -1, 0
	v_mbcnt_hi_u32_b32 v17, -1, v17
	s_nop 0
	v_lshlrev_b32_e32 v17, 2, v17
	v_xor_b32_e32 v17, 0x80, v17
	ds_bpermute_b32 v17, v17, v16
	s_and_saveexec_b64 s[26:27], s[2:3]
	s_cbranch_execz .LBB0_1631
	s_waitcnt lgkmcnt(0)
	v_add_f32_e32 v16, v16, v17
	flat_atomic_add_f32 v[128:129], v16 offset:640
.LBB0_1631:
	s_or_b64 exec, exec, s[26:27]
	s_mov_b64 s[26:27], 0x58000
	v_lshl_add_u64 v[20:21], v[154:155], 0, s[26:27]
	s_waitcnt lgkmcnt(0)
	v_lshl_add_u64 v[16:17], s[0:1], 0, v[20:21]
	s_mov_b64 s[26:27], 0x58100
	s_waitcnt vmcnt(29)
	v_mov_b32_e32 v16, v244
	v_mov_b32_e32 v17, v245
	v_mov_b32_e32 v18, v246
	v_mov_b32_e32 v19, v247
	v_lshlrev_b32_e32 v22, 16, v16
	v_and_b32_e32 v23, 0xffff0000, v16
	v_lshlrev_b32_e32 v16, 16, v17
	v_and_b32_e32 v17, 0xffff0000, v17
	v_lshlrev_b32_e32 v32, 16, v18
	v_and_b32_e32 v33, 0xffff0000, v18
	v_lshlrev_b32_e32 v18, 16, v19
	v_and_b32_e32 v19, 0xffff0000, v19
	v_pk_add_f32 v[16:17], v[14:15], v[16:17]
	v_pk_add_f32 v[14:15], v[12:13], v[22:23]
	v_pk_add_f32 v[18:19], v[10:11], v[18:19]
	v_pk_add_f32 v[22:23], v[8:9], v[32:33]
	v_cvt_pk_bf16_f32 v10, v14, v15
	v_cvt_pk_bf16_f32 v11, v16, v17
	v_cvt_pk_bf16_f32 v12, v22, v23
	v_cvt_pk_bf16_f32 v13, v18, v19
	v_lshl_add_u64 v[8:9], s[8:9], 0, v[20:21]
	global_store_dwordx4 v[8:9], v[10:13], off
	s_nop 1
	v_mul_f32_e32 v10, v15, v15
	v_mul_f32_e32 v11, v17, v17
	v_fmac_f32_e32 v10, v14, v14
	v_fmac_f32_e32 v11, v16, v16
	v_add_f32_e32 v10, v10, v11
	v_mul_f32_e32 v11, v23, v23
	v_mul_f32_e32 v12, v19, v19
	v_fmac_f32_e32 v11, v22, v22
	v_fmac_f32_e32 v12, v18, v18
	v_add_f32_e32 v11, v11, v12
	v_add_f32_e32 v12, v11, v10
	v_pk_mul_f32 v[10:11], v[44:45], v[14:15]
	s_nop 0
	v_cvt_pk_bf16_f32 v14, v10, v11
	v_pk_mul_f32 v[10:11], v[46:47], v[16:17]
	s_nop 0
	v_cvt_pk_bf16_f32 v15, v10, v11
	v_pk_mul_f32 v[10:11], v[40:41], v[22:23]
	s_nop 0
	v_cvt_pk_bf16_f32 v16, v10, v11
	v_pk_mul_f32 v[10:11], v[42:43], v[18:19]
	s_nop 0
	v_cvt_pk_bf16_f32 v17, v10, v11
	v_lshl_add_u64 v[10:11], s[10:11], 0, v[20:21]
	global_store_dwordx4 v[10:11], v[14:17], off
	v_lshl_add_u64 v[10:11], v[154:155], 0, s[26:27]
	s_nop 0
	v_lshl_add_u64 v[14:15], s[0:1], 0, v[10:11]
	s_waitcnt vmcnt(30)
	v_mov_b32_e32 v14, v248
	v_mov_b32_e32 v15, v249
	v_mov_b32_e32 v16, v250
	v_mov_b32_e32 v17, v251
	v_lshlrev_b32_e32 v18, 16, v14
	v_and_b32_e32 v19, 0xffff0000, v14
	v_lshlrev_b32_e32 v14, 16, v15
	v_and_b32_e32 v15, 0xffff0000, v15
	v_lshlrev_b32_e32 v20, 16, v16
	v_and_b32_e32 v21, 0xffff0000, v16
	v_lshlrev_b32_e32 v16, 16, v17
	v_and_b32_e32 v17, 0xffff0000, v17
	v_pk_add_f32 v[6:7], v[6:7], v[14:15]
	v_pk_add_f32 v[4:5], v[4:5], v[18:19]
	v_pk_add_f32 v[2:3], v[2:3], v[16:17]
	v_pk_add_f32 v[0:1], v[0:1], v[20:21]
	v_cvt_pk_bf16_f32 v14, v4, v5
	v_cvt_pk_bf16_f32 v15, v6, v7
	v_cvt_pk_bf16_f32 v16, v0, v1
	v_cvt_pk_bf16_f32 v17, v2, v3
	global_store_dwordx4 v[8:9], v[14:17], off offset:256
	v_pk_mul_f32 v[8:9], v[28:29], v[4:5]
	v_mul_f32_e32 v5, v5, v5
	v_cvt_pk_bf16_f32 v14, v8, v9
	v_pk_mul_f32 v[8:9], v[30:31], v[6:7]
	v_fmac_f32_e32 v5, v4, v4
	v_cvt_pk_bf16_f32 v15, v8, v9
	v_pk_mul_f32 v[8:9], v[24:25], v[0:1]
	v_mul_f32_e32 v1, v1, v1
	v_cvt_pk_bf16_f32 v16, v8, v9
	v_pk_mul_f32 v[8:9], v[26:27], v[2:3]
	v_mul_f32_e32 v4, v7, v7
	v_fmac_f32_e32 v1, v0, v0
	v_mul_f32_e32 v0, v3, v3
	v_cvt_pk_bf16_f32 v17, v8, v9
	v_lshl_add_u64 v[8:9], s[10:11], 0, v[10:11]
	v_fmac_f32_e32 v4, v6, v6
	v_fmac_f32_e32 v0, v2, v2
	global_store_dwordx4 v[8:9], v[14:17], off
	v_add_f32_e32 v4, v5, v4
	v_add_f32_e32 v0, v1, v0
	v_mbcnt_lo_u32_b32 v1, -1, 0
	v_mbcnt_hi_u32_b32 v1, -1, v1
	v_add_f32_e32 v0, v0, v4
	v_lshlrev_b32_e32 v1, 2, v1
	v_add_f32_e32 v0, v12, v0
	v_xor_b32_e32 v1, 64, v1
	ds_bpermute_b32 v1, v1, v0
	s_waitcnt lgkmcnt(0)
	v_add_f32_e32 v0, v0, v1
	v_mbcnt_lo_u32_b32 v1, -1, 0
	v_mbcnt_hi_u32_b32 v1, -1, v1
	s_nop 0
	v_lshlrev_b32_e32 v1, 2, v1
	v_xor_b32_e32 v1, 0x80, v1
	ds_bpermute_b32 v1, v1, v0
	s_and_saveexec_b64 s[26:27], s[2:3]
	s_cbranch_execz .LBB0_1633
	s_waitcnt lgkmcnt(0)
	v_add_f32_e32 v0, v0, v1
	flat_atomic_add_f32 v[128:129], v0 offset:704

.LBB0_1906:
	v_lshl_add_u32 v156, s42, 8, v166
	v_ashrrev_i32_e32 v157, 31, v156
	v_lshlrev_b64 v[158:159], 10, v[156:157]
	v_lshl_add_u64 v[158:159], v[158:159], 0, v[154:155]
	v_lshl_add_u64 v[162:163], v[158:159], 1, s[18:19]
	v_mov_b32_e32 v218, v162
	v_mov_b32_e32 v219, v163
	global_load_dwordx4 v[178:181], v[218:219], off
	global_load_dwordx4 v[182:185], v[218:219], off offset:256
	v_add_co_u32_e32 v222, vcc, 0x8000, v218
	s_nop 1
	v_addc_co_u32_e32 v223, vcc, 0, v219, vcc
	global_load_dwordx4 v[186:189], v[222:223], off
	global_load_dwordx4 v[190:193], v[222:223], off offset:256
	v_add_co_u32_e32 v222, vcc, 0x10000, v218
	s_nop 1
	v_addc_co_u32_e32 v223, vcc, 0, v219, vcc
	global_load_dwordx4 v[194:197], v[222:223], off
	global_load_dwordx4 v[198:201], v[222:223], off offset:256
	v_add_co_u32_e32 v222, vcc, 0x18000, v218
	s_nop 1
	v_addc_co_u32_e32 v223, vcc, 0, v219, vcc
	global_load_dwordx4 v[202:205], v[222:223], off
	global_load_dwordx4 v[206:209], v[222:223], off offset:256
	v_add_co_u32_e32 v222, vcc, 0x40000, v218
	s_nop 1
	v_addc_co_u32_e32 v223, vcc, 0, v219, vcc
	global_load_dwordx4 v[210:213], v[222:223], off
	global_load_dwordx4 v[214:217], v[222:223], off offset:256
	v_add_co_u32_e32 v222, vcc, 0x48000, v218
	s_nop 1
	v_addc_co_u32_e32 v223, vcc, 0, v219, vcc
	global_load_dwordx4 v[226:229], v[222:223], off
	global_load_dwordx4 v[230:233], v[222:223], off offset:256
	v_add_co_u32_e32 v222, vcc, 0x50000, v218
	s_nop 1
	v_addc_co_u32_e32 v223, vcc, 0, v219, vcc
	global_load_dwordx4 v[236:239], v[222:223], off
	global_load_dwordx4 v[240:243], v[222:223], off offset:256
	v_add_co_u32_e32 v222, vcc, 0x58000, v218
	s_nop 1
	v_addc_co_u32_e32 v223, vcc, 0, v219, vcc
	global_load_dwordx4 v[244:247], v[222:223], off
	global_load_dwordx4 v[248:251], v[222:223], off offset:256
	v_readlane_b32 s30, v255, 26
	v_readlane_b32 s31, v255, 27
	s_mov_b64 s[28:29], -1
	s_andn2_b64 vcc, exec, s[30:31]
	v_cndmask_b32_e64 v160, 0, 1, s[30:31]
	v_cmp_ne_u32_e64 s[8:9], 1, v160
	s_waitcnt vmcnt(15)
	v_mov_b32_e32 v170, v178
	v_mov_b32_e32 v171, v179
	v_mov_b32_e32 v172, v180
	v_mov_b32_e32 v173, v181
	v_lshlrev_b32_e32 v160, 16, v170
	v_and_b32_e32 v161, 0xffff0000, v170
	v_lshlrev_b32_e32 v164, 16, v171
	v_and_b32_e32 v165, 0xffff0000, v171
	v_lshlrev_b32_e32 v170, 16, v172
	v_and_b32_e32 v171, 0xffff0000, v172
	v_lshlrev_b32_e32 v172, 16, v173
	v_and_b32_e32 v173, 0xffff0000, v173
	v_pk_add_f32 v[142:143], v[142:143], v[164:165]
	v_pk_add_f32 v[140:141], v[140:141], v[160:161]
	v_pk_add_f32 v[138:139], v[138:139], v[172:173]
	v_pk_add_f32 v[136:137], v[136:137], v[170:171]
	v_lshl_add_u64 v[160:161], v[158:159], 1, s[14:15]
	s_cbranch_vccnz .LBB0_1908
	v_cvt_pk_bf16_f32 v170, v140, v141
	v_cvt_pk_bf16_f32 v171, v142, v143
	v_cvt_pk_bf16_f32 v172, v136, v137
	v_cvt_pk_bf16_f32 v173, v138, v139
	s_mov_b64 s[28:29], 0
	global_store_dwordx4 v[160:161], v[170:173], off

.LBB0_1912:
	s_and_b64 vcc, exec, s[8:9]
	s_mov_b64 s[28:29], -1
	s_waitcnt vmcnt(16)
	v_mov_b32_e32 v136, v182
	v_mov_b32_e32 v137, v183
	v_mov_b32_e32 v138, v184
	v_mov_b32_e32 v139, v185
	v_lshlrev_b32_e32 v140, 16, v136
	v_and_b32_e32 v141, 0xffff0000, v136
	v_lshlrev_b32_e32 v136, 16, v137
	v_and_b32_e32 v137, 0xffff0000, v137
	v_lshlrev_b32_e32 v142, 16, v138
	v_and_b32_e32 v143, 0xffff0000, v138
	v_lshlrev_b32_e32 v138, 16, v139
	v_and_b32_e32 v139, 0xffff0000, v139
	v_pk_add_f32 v[134:135], v[134:135], v[136:137]
	v_pk_add_f32 v[132:133], v[132:133], v[140:141]
	v_pk_add_f32 v[130:131], v[130:131], v[138:139]
	v_pk_add_f32 v[128:129], v[128:129], v[142:143]
	s_cbranch_vccnz .LBB0_1915
	v_cvt_pk_bf16_f32 v136, v132, v133
	v_cvt_pk_bf16_f32 v137, v134, v135
	v_cvt_pk_bf16_f32 v138, v128, v129
	v_cvt_pk_bf16_f32 v139, v130, v131
	global_store_dwordx4 v[160:161], v[136:139], off offset:256
	s_cbranch_execz .LBB0_1916

.LBB0_1920:
	v_or_b32_e32 v128, 16, v156
	s_waitcnt lgkmcnt(0)
	v_ashrrev_i32_e32 v129, 31, v128
	v_lshlrev_b64 v[130:131], 10, v[128:129]
	v_lshl_add_u64 v[130:131], v[130:131], 0, v[154:155]
	v_lshl_add_u64 v[134:135], v[130:131], 1, s[18:19]
	s_mov_b64 s[28:29], -1
	s_and_b64 vcc, exec, s[8:9]
	s_waitcnt vmcnt(17)
	v_mov_b32_e32 v136, v186
	v_mov_b32_e32 v137, v187
	v_mov_b32_e32 v138, v188
	v_mov_b32_e32 v139, v189
	v_lshlrev_b32_e32 v132, 16, v136
	v_and_b32_e32 v133, 0xffff0000, v136
	v_lshlrev_b32_e32 v136, 16, v137
	v_and_b32_e32 v137, 0xffff0000, v137
	v_lshlrev_b32_e32 v140, 16, v138
	v_and_b32_e32 v141, 0xffff0000, v138
	v_lshlrev_b32_e32 v138, 16, v139
	v_and_b32_e32 v139, 0xffff0000, v139
	v_pk_add_f32 v[126:127], v[126:127], v[136:137]
	v_pk_add_f32 v[124:125], v[124:125], v[132:133]
	v_pk_add_f32 v[122:123], v[122:123], v[138:139]
	v_pk_add_f32 v[120:121], v[120:121], v[140:141]
	v_lshl_add_u64 v[132:133], v[130:131], 1, s[14:15]
	s_cbranch_vccnz .LBB0_1922
	v_cvt_pk_bf16_f32 v136, v124, v125
	v_cvt_pk_bf16_f32 v137, v126, v127
	v_cvt_pk_bf16_f32 v138, v120, v121
	v_cvt_pk_bf16_f32 v139, v122, v123
	s_mov_b64 s[28:29], 0
	global_store_dwordx4 v[132:133], v[136:139], off

.LBB0_1926:
	s_and_b64 vcc, exec, s[8:9]
	s_mov_b64 s[28:29], -1
	s_waitcnt vmcnt(18)
	v_mov_b32_e32 v120, v190
	v_mov_b32_e32 v121, v191
	v_mov_b32_e32 v122, v192
	v_mov_b32_e32 v123, v193
	v_lshlrev_b32_e32 v124, 16, v120
	v_and_b32_e32 v125, 0xffff0000, v120
	v_lshlrev_b32_e32 v120, 16, v121
	v_and_b32_e32 v121, 0xffff0000, v121
	v_lshlrev_b32_e32 v126, 16, v122
	v_and_b32_e32 v127, 0xffff0000, v122
	v_lshlrev_b32_e32 v122, 16, v123
	v_and_b32_e32 v123, 0xffff0000, v123
	v_pk_add_f32 v[118:119], v[118:119], v[120:121]
	v_pk_add_f32 v[116:117], v[116:117], v[124:125]
	v_pk_add_f32 v[114:115], v[114:115], v[122:123]
	v_pk_add_f32 v[112:113], v[112:113], v[126:127]
	s_cbranch_vccnz .LBB0_1929
	v_cvt_pk_bf16_f32 v120, v116, v117
	v_cvt_pk_bf16_f32 v121, v118, v119
	v_cvt_pk_bf16_f32 v122, v112, v113
	v_cvt_pk_bf16_f32 v123, v114, v115
	global_store_dwordx4 v[132:133], v[120:123], off offset:256
	s_cbranch_execz .LBB0_1930

.LBB0_1934:
	v_or_b32_e32 v112, 32, v156
	s_waitcnt lgkmcnt(0)
	v_ashrrev_i32_e32 v113, 31, v112
	v_lshlrev_b64 v[114:115], 10, v[112:113]
	v_lshl_add_u64 v[114:115], v[114:115], 0, v[154:155]
	v_lshl_add_u64 v[118:119], v[114:115], 1, s[18:19]
	s_mov_b64 s[28:29], -1
	s_and_b64 vcc, exec, s[8:9]
	s_waitcnt vmcnt(19)
	v_mov_b32_e32 v120, v194
	v_mov_b32_e32 v121, v195
	v_mov_b32_e32 v122, v196
	v_mov_b32_e32 v123, v197
	v_lshlrev_b32_e32 v116, 16, v120
	v_and_b32_e32 v117, 0xffff0000, v120
	v_lshlrev_b32_e32 v120, 16, v121
	v_and_b32_e32 v121, 0xffff0000, v121
	v_lshlrev_b32_e32 v124, 16, v122
	v_and_b32_e32 v125, 0xffff0000, v122
	v_lshlrev_b32_e32 v122, 16, v123
	v_and_b32_e32 v123, 0xffff0000, v123
	v_pk_add_f32 v[110:111], v[110:111], v[120:121]
	v_pk_add_f32 v[108:109], v[108:109], v[116:117]
	v_pk_add_f32 v[106:107], v[106:107], v[122:123]
	v_pk_add_f32 v[104:105], v[104:105], v[124:125]
	v_lshl_add_u64 v[116:117], v[114:115], 1, s[14:15]
	s_cbranch_vccnz .LBB0_1936
	v_cvt_pk_bf16_f32 v120, v108, v109
	v_cvt_pk_bf16_f32 v121, v110, v111
	v_cvt_pk_bf16_f32 v122, v104, v105
	v_cvt_pk_bf16_f32 v123, v106, v107
	s_mov_b64 s[28:29], 0
	global_store_dwordx4 v[116:117], v[120:123], off

.LBB0_1940:
	s_and_b64 vcc, exec, s[8:9]
	s_mov_b64 s[28:29], -1
	s_waitcnt vmcnt(20)
	v_mov_b32_e32 v104, v198
	v_mov_b32_e32 v105, v199
	v_mov_b32_e32 v106, v200
	v_mov_b32_e32 v107, v201
	v_lshlrev_b32_e32 v108, 16, v104
	v_and_b32_e32 v109, 0xffff0000, v104
	v_lshlrev_b32_e32 v104, 16, v105
	v_and_b32_e32 v105, 0xffff0000, v105
	v_lshlrev_b32_e32 v110, 16, v106
	v_and_b32_e32 v111, 0xffff0000, v106
	v_lshlrev_b32_e32 v106, 16, v107
	v_and_b32_e32 v107, 0xffff0000, v107
	v_pk_add_f32 v[102:103], v[102:103], v[104:105]
	v_pk_add_f32 v[100:101], v[100:101], v[108:109]
	v_pk_add_f32 v[98:99], v[98:99], v[106:107]
	v_pk_add_f32 v[96:97], v[96:97], v[110:111]
	s_cbranch_vccnz .LBB0_1943
	v_cvt_pk_bf16_f32 v104, v100, v101
	v_cvt_pk_bf16_f32 v105, v102, v103
	v_cvt_pk_bf16_f32 v106, v96, v97
	v_cvt_pk_bf16_f32 v107, v98, v99
	global_store_dwordx4 v[116:117], v[104:107], off offset:256
	s_cbranch_execz .LBB0_1944

.LBB0_1948:
	v_or_b32_e32 v96, 48, v156
	s_waitcnt lgkmcnt(0)
	v_ashrrev_i32_e32 v97, 31, v96
	v_lshlrev_b64 v[98:99], 10, v[96:97]
	v_lshl_add_u64 v[98:99], v[98:99], 0, v[154:155]
	v_lshl_add_u64 v[102:103], v[98:99], 1, s[18:19]
	s_mov_b64 s[28:29], -1
	s_and_b64 vcc, exec, s[8:9]
	s_waitcnt vmcnt(21)
	v_mov_b32_e32 v104, v202
	v_mov_b32_e32 v105, v203
	v_mov_b32_e32 v106, v204
	v_mov_b32_e32 v107, v205
	v_lshlrev_b32_e32 v100, 16, v104
	v_and_b32_e32 v101, 0xffff0000, v104
	v_lshlrev_b32_e32 v104, 16, v105
	v_and_b32_e32 v105, 0xffff0000, v105
	v_lshlrev_b32_e32 v108, 16, v106
	v_and_b32_e32 v109, 0xffff0000, v106
	v_lshlrev_b32_e32 v106, 16, v107
	v_and_b32_e32 v107, 0xffff0000, v107
	v_pk_add_f32 v[94:95], v[94:95], v[104:105]
	v_pk_add_f32 v[92:93], v[92:93], v[100:101]
	v_pk_add_f32 v[90:91], v[90:91], v[106:107]
	v_pk_add_f32 v[88:89], v[88:89], v[108:109]
	v_lshl_add_u64 v[100:101], v[98:99], 1, s[14:15]
	s_cbranch_vccnz .LBB0_1950
	v_cvt_pk_bf16_f32 v104, v92, v93
	v_cvt_pk_bf16_f32 v105, v94, v95
	v_cvt_pk_bf16_f32 v106, v88, v89
	v_cvt_pk_bf16_f32 v107, v90, v91
	s_mov_b64 s[28:29], 0
	global_store_dwordx4 v[100:101], v[104:107], off

.LBB0_1954:
	s_and_b64 vcc, exec, s[8:9]
	s_mov_b64 s[28:29], -1
	s_waitcnt vmcnt(22)
	v_mov_b32_e32 v88, v206
	v_mov_b32_e32 v89, v207
	v_mov_b32_e32 v90, v208
	v_mov_b32_e32 v91, v209
	v_lshlrev_b32_e32 v92, 16, v88
	v_and_b32_e32 v93, 0xffff0000, v88
	v_lshlrev_b32_e32 v88, 16, v89
	v_and_b32_e32 v89, 0xffff0000, v89
	v_lshlrev_b32_e32 v94, 16, v90
	v_and_b32_e32 v95, 0xffff0000, v90
	v_lshlrev_b32_e32 v90, 16, v91
	v_and_b32_e32 v91, 0xffff0000, v91
	v_pk_add_f32 v[86:87], v[86:87], v[88:89]
	v_pk_add_f32 v[84:85], v[84:85], v[92:93]
	v_pk_add_f32 v[82:83], v[82:83], v[90:91]
	v_pk_add_f32 v[80:81], v[80:81], v[94:95]
	s_cbranch_vccnz .LBB0_1957
	v_cvt_pk_bf16_f32 v88, v84, v85
	v_cvt_pk_bf16_f32 v89, v86, v87
	v_cvt_pk_bf16_f32 v90, v80, v81
	v_cvt_pk_bf16_f32 v91, v82, v83
	global_store_dwordx4 v[100:101], v[88:91], off offset:256
	s_cbranch_execz .LBB0_1958

.LBB0_1962:
	v_add_u32_e32 v80, 0x80, v156
	s_waitcnt lgkmcnt(0)
	v_ashrrev_i32_e32 v81, 31, v80
	v_lshlrev_b64 v[82:83], 10, v[80:81]
	v_lshl_add_u64 v[82:83], v[82:83], 0, v[154:155]
	v_lshl_add_u64 v[86:87], v[82:83], 1, s[18:19]
	s_mov_b64 s[28:29], -1
	s_and_b64 vcc, exec, s[8:9]
	s_waitcnt vmcnt(23)
	v_mov_b32_e32 v88, v210
	v_mov_b32_e32 v89, v211
	v_mov_b32_e32 v90, v212
	v_mov_b32_e32 v91, v213
	v_lshlrev_b32_e32 v84, 16, v88
	v_and_b32_e32 v85, 0xffff0000, v88
	v_lshlrev_b32_e32 v88, 16, v89
	v_and_b32_e32 v89, 0xffff0000, v89
	v_lshlrev_b32_e32 v92, 16, v90
	v_and_b32_e32 v93, 0xffff0000, v90
	v_lshlrev_b32_e32 v90, 16, v91
	v_and_b32_e32 v91, 0xffff0000, v91
	v_pk_add_f32 v[78:79], v[78:79], v[88:89]
	v_pk_add_f32 v[76:77], v[76:77], v[84:85]
	v_pk_add_f32 v[74:75], v[74:75], v[90:91]
	v_pk_add_f32 v[72:73], v[72:73], v[92:93]
	v_lshl_add_u64 v[84:85], v[82:83], 1, s[14:15]
	s_cbranch_vccnz .LBB0_1964
	v_cvt_pk_bf16_f32 v88, v76, v77
	v_cvt_pk_bf16_f32 v89, v78, v79
	v_cvt_pk_bf16_f32 v90, v72, v73
	v_cvt_pk_bf16_f32 v91, v74, v75
	s_mov_b64 s[28:29], 0
	global_store_dwordx4 v[84:85], v[88:91], off

.LBB0_1968:
	s_and_b64 vcc, exec, s[8:9]
	s_mov_b64 s[28:29], -1
	s_waitcnt vmcnt(24)
	v_mov_b32_e32 v72, v214
	v_mov_b32_e32 v73, v215
	v_mov_b32_e32 v74, v216
	v_mov_b32_e32 v75, v217
	v_lshlrev_b32_e32 v76, 16, v72
	v_and_b32_e32 v77, 0xffff0000, v72
	v_lshlrev_b32_e32 v72, 16, v73
	v_and_b32_e32 v73, 0xffff0000, v73
	v_lshlrev_b32_e32 v78, 16, v74
	v_and_b32_e32 v79, 0xffff0000, v74
	v_lshlrev_b32_e32 v74, 16, v75
	v_and_b32_e32 v75, 0xffff0000, v75
	v_pk_add_f32 v[62:63], v[62:63], v[72:73]
	v_pk_add_f32 v[60:61], v[60:61], v[76:77]
	v_pk_add_f32 v[58:59], v[58:59], v[74:75]
	v_pk_add_f32 v[56:57], v[56:57], v[78:79]
	s_cbranch_vccnz .LBB0_1971
	v_cvt_pk_bf16_f32 v72, v60, v61
	v_cvt_pk_bf16_f32 v73, v62, v63
	v_cvt_pk_bf16_f32 v74, v56, v57
	v_cvt_pk_bf16_f32 v75, v58, v59
	global_store_dwordx4 v[84:85], v[72:75], off offset:256
	s_cbranch_execz .LBB0_1972

.LBB0_1976:
	v_add_u32_e32 v56, 0x90, v156
	s_waitcnt lgkmcnt(0)
	v_ashrrev_i32_e32 v57, 31, v56
	v_lshlrev_b64 v[58:59], 10, v[56:57]
	v_lshl_add_u64 v[58:59], v[58:59], 0, v[154:155]
	v_lshl_add_u64 v[62:63], v[58:59], 1, s[18:19]
	s_mov_b64 s[28:29], -1
	s_and_b64 vcc, exec, s[8:9]
	s_waitcnt vmcnt(25)
	v_mov_b32_e32 v72, v226
	v_mov_b32_e32 v73, v227
	v_mov_b32_e32 v74, v228
	v_mov_b32_e32 v75, v229
	v_lshlrev_b32_e32 v60, 16, v72
	v_and_b32_e32 v61, 0xffff0000, v72
	v_lshlrev_b32_e32 v72, 16, v73
	v_and_b32_e32 v73, 0xffff0000, v73
	v_lshlrev_b32_e32 v76, 16, v74
	v_and_b32_e32 v77, 0xffff0000, v74
	v_lshlrev_b32_e32 v74, 16, v75
	v_and_b32_e32 v75, 0xffff0000, v75
	v_pk_add_f32 v[46:47], v[46:47], v[72:73]
	v_pk_add_f32 v[44:45], v[44:45], v[60:61]
	v_pk_add_f32 v[42:43], v[42:43], v[74:75]
	v_pk_add_f32 v[40:41], v[40:41], v[76:77]
	v_lshl_add_u64 v[60:61], v[58:59], 1, s[14:15]
	s_cbranch_vccnz .LBB0_1978
	v_cvt_pk_bf16_f32 v72, v44, v45
	v_cvt_pk_bf16_f32 v73, v46, v47
	v_cvt_pk_bf16_f32 v74, v40, v41
	v_cvt_pk_bf16_f32 v75, v42, v43
	s_mov_b64 s[28:29], 0
	global_store_dwordx4 v[60:61], v[72:75], off

.LBB0_1982:
	s_and_b64 vcc, exec, s[8:9]
	s_mov_b64 s[28:29], -1
	s_waitcnt vmcnt(26)
	v_mov_b32_e32 v40, v230
	v_mov_b32_e32 v41, v231
	v_mov_b32_e32 v42, v232
	v_mov_b32_e32 v43, v233
	v_lshlrev_b32_e32 v44, 16, v40
	v_and_b32_e32 v45, 0xffff0000, v40
	v_lshlrev_b32_e32 v40, 16, v41
	v_and_b32_e32 v41, 0xffff0000, v41
	v_lshlrev_b32_e32 v46, 16, v42
	v_and_b32_e32 v47, 0xffff0000, v42
	v_lshlrev_b32_e32 v42, 16, v43
	v_and_b32_e32 v43, 0xffff0000, v43
	v_pk_add_f32 v[38:39], v[38:39], v[40:41]
	v_pk_add_f32 v[36:37], v[36:37], v[44:45]
	v_pk_add_f32 v[34:35], v[34:35], v[42:43]
	v_pk_add_f32 v[32:33], v[32:33], v[46:47]
	s_cbranch_vccnz .LBB0_1985
	v_cvt_pk_bf16_f32 v40, v36, v37
	v_cvt_pk_bf16_f32 v41, v38, v39
	v_cvt_pk_bf16_f32 v42, v32, v33
	v_cvt_pk_bf16_f32 v43, v34, v35
	global_store_dwordx4 v[60:61], v[40:43], off offset:256
	s_cbranch_execz .LBB0_1986

.LBB0_1990:
	v_add_u32_e32 v32, 0xa0, v156
	s_waitcnt lgkmcnt(0)
	v_ashrrev_i32_e32 v33, 31, v32
	v_lshlrev_b64 v[34:35], 10, v[32:33]
	v_lshl_add_u64 v[34:35], v[34:35], 0, v[154:155]
	v_lshl_add_u64 v[38:39], v[34:35], 1, s[18:19]
	s_mov_b64 s[28:29], -1
	s_and_b64 vcc, exec, s[8:9]
	s_waitcnt vmcnt(27)
	v_mov_b32_e32 v40, v236
	v_mov_b32_e32 v41, v237
	v_mov_b32_e32 v42, v238
	v_mov_b32_e32 v43, v239
	v_lshlrev_b32_e32 v36, 16, v40
	v_and_b32_e32 v37, 0xffff0000, v40
	v_lshlrev_b32_e32 v40, 16, v41
	v_and_b32_e32 v41, 0xffff0000, v41
	v_lshlrev_b32_e32 v44, 16, v42
	v_and_b32_e32 v45, 0xffff0000, v42
	v_lshlrev_b32_e32 v42, 16, v43
	v_and_b32_e32 v43, 0xffff0000, v43
	v_pk_add_f32 v[30:31], v[30:31], v[40:41]
	v_pk_add_f32 v[28:29], v[28:29], v[36:37]
	v_pk_add_f32 v[26:27], v[26:27], v[42:43]
	v_pk_add_f32 v[24:25], v[24:25], v[44:45]
	v_lshl_add_u64 v[36:37], v[34:35], 1, s[14:15]
	s_cbranch_vccnz .LBB0_1992
	v_cvt_pk_bf16_f32 v40, v28, v29
	v_cvt_pk_bf16_f32 v41, v30, v31
	v_cvt_pk_bf16_f32 v42, v24, v25
	v_cvt_pk_bf16_f32 v43, v26, v27
	s_mov_b64 s[28:29], 0
	global_store_dwordx4 v[36:37], v[40:43], off

.LBB0_1996:
	s_and_b64 vcc, exec, s[8:9]
	s_mov_b64 s[28:29], -1
	s_waitcnt vmcnt(28)
	v_mov_b32_e32 v24, v240
	v_mov_b32_e32 v25, v241
	v_mov_b32_e32 v26, v242
	v_mov_b32_e32 v27, v243
	v_lshlrev_b32_e32 v28, 16, v24
	v_and_b32_e32 v29, 0xffff0000, v24
	v_lshlrev_b32_e32 v24, 16, v25
	v_and_b32_e32 v25, 0xffff0000, v25
	v_lshlrev_b32_e32 v30, 16, v26
	v_and_b32_e32 v31, 0xffff0000, v26
	v_lshlrev_b32_e32 v26, 16, v27
	v_and_b32_e32 v27, 0xffff0000, v27
	v_pk_add_f32 v[22:23], v[22:23], v[24:25]
	v_pk_add_f32 v[20:21], v[20:21], v[28:29]
	v_pk_add_f32 v[18:19], v[18:19], v[26:27]
	v_pk_add_f32 v[16:17], v[16:17], v[30:31]
	s_cbranch_vccnz .LBB0_1999
	v_cvt_pk_bf16_f32 v24, v20, v21
	v_cvt_pk_bf16_f32 v25, v22, v23
	v_cvt_pk_bf16_f32 v26, v16, v17
	v_cvt_pk_bf16_f32 v27, v18, v19
	global_store_dwordx4 v[36:37], v[24:27], off offset:256
	s_cbranch_execz .LBB0_2000

.LBB0_2004:
	v_add_u32_e32 v16, 0xb0, v156
	s_waitcnt lgkmcnt(0)
	v_ashrrev_i32_e32 v17, 31, v16
	v_lshlrev_b64 v[18:19], 10, v[16:17]
	v_lshl_add_u64 v[18:19], v[18:19], 0, v[154:155]
	v_lshl_add_u64 v[22:23], v[18:19], 1, s[18:19]
	s_mov_b64 s[28:29], -1
	s_and_b64 vcc, exec, s[8:9]
	s_waitcnt vmcnt(29)
	v_mov_b32_e32 v24, v244
	v_mov_b32_e32 v25, v245
	v_mov_b32_e32 v26, v246
	v_mov_b32_e32 v27, v247
	v_lshlrev_b32_e32 v20, 16, v24
	v_and_b32_e32 v21, 0xffff0000, v24
	v_lshlrev_b32_e32 v24, 16, v25
	v_and_b32_e32 v25, 0xffff0000, v25
	v_lshlrev_b32_e32 v28, 16, v26
	v_and_b32_e32 v29, 0xffff0000, v26
	v_lshlrev_b32_e32 v26, 16, v27
	v_and_b32_e32 v27, 0xffff0000, v27
	v_pk_add_f32 v[14:15], v[14:15], v[24:25]
	v_pk_add_f32 v[12:13], v[12:13], v[20:21]
	v_pk_add_f32 v[10:11], v[10:11], v[26:27]
	v_pk_add_f32 v[8:9], v[8:9], v[28:29]
	v_lshl_add_u64 v[20:21], v[18:19], 1, s[14:15]
	s_cbranch_vccnz .LBB0_2006
	v_cvt_pk_bf16_f32 v24, v12, v13
	v_cvt_pk_bf16_f32 v25, v14, v15
	v_cvt_pk_bf16_f32 v26, v8, v9
	v_cvt_pk_bf16_f32 v27, v10, v11
	s_mov_b64 s[28:29], 0
	global_store_dwordx4 v[20:21], v[24:27], off

.LBB0_2010:
	s_and_b64 vcc, exec, s[8:9]
	s_mov_b64 s[8:9], -1
	s_waitcnt vmcnt(30)
	v_mov_b32_e32 v8, v248
	v_mov_b32_e32 v9, v249
	v_mov_b32_e32 v10, v250
	v_mov_b32_e32 v11, v251
	v_lshlrev_b32_e32 v12, 16, v8
	v_and_b32_e32 v13, 0xffff0000, v8
	v_lshlrev_b32_e32 v8, 16, v9
	v_and_b32_e32 v9, 0xffff0000, v9
	v_lshlrev_b32_e32 v14, 16, v10
	v_and_b32_e32 v15, 0xffff0000, v10
	v_lshlrev_b32_e32 v10, 16, v11
	v_and_b32_e32 v11, 0xffff0000, v11
	v_pk_add_f32 v[6:7], v[6:7], v[8:9]
	v_pk_add_f32 v[4:5], v[4:5], v[12:13]
	v_pk_add_f32 v[2:3], v[2:3], v[10:11]
	v_pk_add_f32 v[0:1], v[0:1], v[14:15]
	s_cbranch_vccnz .LBB0_2016
	v_cvt_pk_bf16_f32 v8, v4, v5
	v_cvt_pk_bf16_f32 v9, v6, v7
	v_cvt_pk_bf16_f32 v10, v0, v1
	v_cvt_pk_bf16_f32 v11, v2, v3
	global_store_dwordx4 v[20:21], v[8:11], off offset:256
	s_cbranch_execz .LBB0_2017
